# v36 with the P4 weight-conversion share indexed by the original (XCD-striped) workgroup id
# speedup vs baseline: 1.0018x; 1.0018x over previous
; #define LAS __attribute__((address_space(3)))
; DI float bf2f(unsigned short u) { return __uint_as_float(((unsigned)u) << 16); }
; DI float gamma_of(int h) { return 1.0f - exp2f(-5.0f - (float)h); }
; DI void ret_decode_unit(LAS unsigned char* lds, const bf16_t* Z, const float* S0, float* S1, bf16_t* MIX, const float* rng, int b, int h, int tid) {
;     LAS float* qv = (LAS float*)lds; LAS float* red = qv + 768;
;     const int lane = tid & 63, wid = tid >> 6;
;     const bf16_t* zrow = Z + (size_t)(LP + b) * INW;
;     if (tid < 256) { qv[tid] = bf2f(zrow[C_RQ + h * 256 + tid]); qv[256 + tid] = bf2f(zrow[C_RK + h * 256 + tid]); qv[512 + tid] = bf2f(zrow[C_RV + h * 256 + tid]); }
;     __syncthreads();
;     const float gm = gamma_of(h);
;     const f32x4 v4 = *(const LAS f32x4*)(qv + 512 + 4 * lane);
;     f32x4 acc = {0.f, 0.f, 0.f, 0.f};
;     const size_t off = ((size_t)(b * 4 + h) * 256 + wid * 32) * 256 + 4 * lane;
;     const float* s0 = S0 + off; float* s1 = S1 + off;
; __global__ void __launch_bounds__(512, 2) fwd_kernel(Args a) {
;     ...
;     if (IN(2)) for (int rep_ = 0; rep_ < 1 + ((DUPMASK >> 2) & 1); ++rep_) { if (rep_) xcd_barrier(bar);
;         if (bx & 1) for (int u = bx; u < 256; u += G) ret_decode_unit(lds, Z, state0, out + O_SS, MIX, rng, u >> 2, u & 3, tid);
;         for (int u = bx; u < 256; u += G) ret_step1(lds, Z, KV, u >> 2, u & 3, tid);
;         if (!(bx & 1)) for (int u = bx; u < 256; u += G) ret_decode_unit(lds, Z, state0, out + O_SS, MIX, rng, u >> 2, u & 3, tid);
;     }
.LBB0_226:
	s_mov_b32 s32, s92
	s_and_b32 s98, s92, 7
	s_lshl_b32 s98, s98, 5
	s_lshr_b32 s99, s92, 3
	s_or_b32 s92, s98, s99
	s_cmp_lt_i32 s62, 3
	s_cselect_b64 s[2:3], -1, 0
	s_add_u32 s56, s60, 0x8000000
	s_addc_u32 s57, s61, 0
	s_add_u32 s4, s60, 0xfc00000
	s_addc_u32 s5, s61, 0
	v_writelane_b32 v254, s4, 23
	s_and_b64 s[10:11], s[2:3], s[0:1]
	s_andn2_b64 vcc, exec, s[10:11]
	v_writelane_b32 v254, s5, 24
	v_lshrrev_b32_e32 v252, 6, v253
	v_cmp_gt_u32_e64 s[0:1], 64, v253
	s_cbranch_vccnz .LBB0_250
	s_bitcmp0_b32 s92, 2
	v_readlane_b32 s68, v254, 7
	s_cselect_b64 s[14:15], -1, 0
	s_cmpk_gt_i32 s92, 0xff
	v_readlane_b32 s82, v254, 21
	v_lshlrev_b32_e32 v0, 2, v253
	s_cselect_b64 s[2:3], -1, 0
	v_readlane_b32 s83, v254, 22
	s_add_u32 s12, s82, 0x5220000
	v_and_b32_e32 v147, 0xfc, v0
	v_readlane_b32 s72, v254, 11
	v_readlane_b32 s73, v254, 12
	s_addc_u32 s13, s83, 0
	s_movk_i32 s4, 0x100
	v_add_u32_e32 v146, 0, v0
	v_lshlrev_b32_e32 v20, 2, v147
	v_mov_b32_e32 v21, 0
	v_lshl_add_u32 v149, v252, 7, 0
	v_mul_u32_u24_e32 v0, 0x380, v252
	s_or_b64 s[2:3], s[14:15], s[2:3]
	s_mov_b32 s17, 0
	v_add_u32_e32 v144, 0x900, v253
	v_add_u32_e32 v145, 0xd00, v253
	v_cmp_gt_u32_e64 s[6:7], s4, v253
	v_add_u32_e32 v148, 0, v20
	v_lshl_or_b32 v128, v252, 13, v147
	v_mov_b32_e32 v129, v21
	v_add3_u32 v150, v149, v0, v20
	v_lshl_add_u64 v[130:131], s[72:73], 0, v[20:21]
	s_and_b64 vcc, exec, s[2:3]
	v_readlane_b32 s69, v254, 8
	v_readlane_b32 s70, v254, 9
	v_readlane_b32 s71, v254, 10
	v_readlane_b32 s74, v254, 13
	v_readlane_b32 s75, v254, 14
	v_readlane_b32 s76, v254, 15
	v_readlane_b32 s77, v254, 16
	v_readlane_b32 s78, v254, 17
	v_readlane_b32 s79, v254, 18
	v_readlane_b32 s80, v254, 19
	v_readlane_b32 s81, v254, 20
	s_cbranch_vccnz .LBB0_236
	v_mbcnt_lo_u32_b32 v0, -1, 0
	v_mov_b32_e32 v30, 0x42800000
	v_mov_b32_e32 v31, 0x358637bd
	v_mbcnt_hi_u32_b32 v32, -1, v0
	s_mov_b32 s18, s92
	s_branch .LBB0_230
